# NSA item epilogue: the seven per-chunk g_out gain loads issued together instead of load+wait per chunk
# speedup vs baseline: 1.0457x; 1.0005x over previous
; __device__ __forceinline__ float bf2f(bf16_t h) { return __uint_as_float((unsigned)h << 16); }
; __device__ __forceinline__ float sum32(float v) { auto rr = __builtin_amdgcn_permlane32_swap(__float_as_uint(v), __float_as_uint(v), false, false); return __uint_as_float(rr[0]) + __uint_as_float(rr[1]); }
; __device__ __forceinline__ void nsa_item(const NsaArgs& A, int b, int tl, LAS unsigned char* lds, int tid) {
;     ...
;     for (int br = 0; br < 3; ++br) { const float x = bf2f(base[(size_t)tq * NP + C_GT + head * 3 + br]) + A.b_gate[head * 3 + br]; gl[br] = 1.f / (1.f + __expf(-x)); }
;     ...
;         const float sc = gl[2] / l;
; #pragma unroll
;         for (int i = 0; i < 16; ++i) { of0[i] = park[i * 64] + sc * o0[i]; of1[i] = park[(16 + i) * 64] + sc * o1[i]; }
;     }
;     {
;         float ss = 0.f;
; #pragma unroll
;         for (int i = 0; i < 16; ++i) ss += of0[i] * of0[i] + of1[i] * of1[i];
;         ss = sum32(ss);
;         const float rs = rsqrtf(ss * (1.f / 64.f) + EPS); const float* go = A.g_out + head * 64; bf16_t* dst = A.groups + token * DM + head * 64;
.LBB0_1153:
	v_lshlrev_b32_e32 v0, 16, v91
	v_add_f32_e32 v0, v90, v0
	v_mul_f32_e32 v0, 0xbfb8aa3b, v0
	v_exp_f32_e32 v0, v0
	v_readlane_b32 s4, v255, 17
	v_readlane_b32 s5, v255, 18
	v_lshlrev_b32_e32 v70, 2, v133
	v_add_f32_e32 v0, 1.0, v0
	v_div_scale_f32 v2, s[0:1], v0, v0, 1.0
	v_rcp_f32_e32 v3, v2
	v_readlane_b32 s6, v253, 25
	v_readlane_b32 s7, v253, 26
	v_fma_f32 v4, -v2, v3, 1.0
	v_fmac_f32_e32 v3, v4, v3
	v_div_scale_f32 v4, vcc, 1.0, v0, 1.0
	v_mul_f32_e32 v5, v4, v3
	v_fma_f32 v6, -v2, v5, v4
	v_fmac_f32_e32 v5, v6, v3
	v_fma_f32 v2, -v2, v5, v4
	v_div_fmas_f32 v2, v2, v3, v5
	v_div_fixup_f32 v0, v2, v0, 1.0
	v_div_scale_f32 v2, s[0:1], v107, v107, v0
	v_rcp_f32_e32 v3, v2
	s_lshl_b32 s0, s27, 2
	s_add_u32 s0, s4, s0
	s_addc_u32 s1, s5, 0
	v_fma_f32 v4, -v2, v3, 1.0
	v_fmac_f32_e32 v3, v4, v3
	v_div_scale_f32 v4, vcc, v0, v107, v0
	v_mul_f32_e32 v5, v4, v3
	v_fma_f32 v6, -v2, v5, v4
	v_fmac_f32_e32 v5, v6, v3
	v_fma_f32 v2, -v2, v5, v4
	v_div_fmas_f32 v2, v2, v3, v5
	v_div_fixup_f32 v8, v2, v107, v0
	ds_read2st64_b32 v[6:7], v153 offset0:140 offset1:141
	ds_read2st64_b32 v[24:25], v153 offset0:156 offset1:157
	ds_read2st64_b32 v[68:69], v153 offset0:142 offset1:143
	ds_read2st64_b32 v[66:67], v153 offset0:158 offset1:159
	ds_read2st64_b32 v[30:31], v153 offset0:144 offset1:145
	ds_read2st64_b32 v[26:27], v153 offset0:160 offset1:161
	ds_read2st64_b32 v[32:33], v153 offset0:146 offset1:147
	ds_read2st64_b32 v[28:29], v153 offset0:162 offset1:163
	ds_read2st64_b32 v[20:21], v153 offset0:148 offset1:149
	ds_read2st64_b32 v[16:17], v153 offset0:164 offset1:165
	ds_read2st64_b32 v[22:23], v153 offset0:150 offset1:151
	ds_read2st64_b32 v[18:19], v153 offset0:166 offset1:167
	ds_read2st64_b32 v[14:15], v153 offset0:152 offset1:153
	ds_read2st64_b32 v[12:13], v153 offset0:168 offset1:169
	ds_read2st64_b32 v[2:3], v153 offset0:154 offset1:155
	ds_read2st64_b32 v[10:11], v153 offset0:170 offset1:171
	s_lshl_b32 s4, s18, 23
	s_add_u32 s4, s6, s4
	s_addc_u32 s5, s7, 0
	s_waitcnt lgkmcnt(1)
	v_pk_fma_f32 v[4:5], v[8:9], v[48:49], v[2:3] op_sel_hi:[0,1,1]
	s_waitcnt lgkmcnt(0)
	v_pk_fma_f32 v[2:3], v[8:9], v[64:65], v[10:11] op_sel_hi:[0,1,1]
	v_pk_fma_f32 v[64:65], v[8:9], v[36:37], v[68:69] op_sel_hi:[0,1,1]
	v_pk_fma_f32 v[68:69], v[8:9], v[34:35], v[6:7] op_sel_hi:[0,1,1]
	global_load_dwordx4 v[34:37], v70, s[0:1]
	v_lshlrev_b64 v[48:49], 11, v[102:103]
	v_lshl_add_u64 v[48:49], s[4:5], 0, v[48:49]
	s_lshl_b32 s30, s27, 1
	v_lshl_add_u64 v[48:49], v[48:49], 0, s[30:31]
	v_lshlrev_b32_e32 v0, 1, v133
	v_pk_fma_f32 v[24:25], v[8:9], v[50:51], v[24:25] op_sel_hi:[0,1,1]
	v_lshl_add_u64 v[6:7], v[48:49], 0, v[0:1]
	v_pk_fma_f32 v[48:49], v[8:9], v[52:53], v[66:67] op_sel_hi:[0,1,1]
	v_pk_mul_f32 v[50:51], v[24:25], v[24:25]
	v_pk_mul_f32 v[52:53], v[48:49], v[48:49]
	v_pk_fma_f32 v[50:51], v[68:69], v[68:69], v[50:51]
	v_pk_fma_f32 v[52:53], v[64:65], v[64:65], v[52:53]
	v_pk_add_f32 v[50:51], v[50:51], v[50:51] op_sel:[0,1] op_sel_hi:[1,0]
	v_pk_fma_f32 v[26:27], v[8:9], v[54:55], v[26:27] op_sel_hi:[0,1,1]
	v_pk_add_f32 v[50:51], v[50:51], v[52:53]
	v_pk_fma_f32 v[32:33], v[8:9], v[40:41], v[32:33] op_sel_hi:[0,1,1]
	v_pk_fma_f32 v[30:31], v[8:9], v[38:39], v[30:31] op_sel_hi:[0,1,1]
	v_pk_mul_f32 v[40:41], v[26:27], v[26:27]
	v_pk_add_f32 v[50:51], v[50:51], v[52:53] op_sel:[0,1] op_sel_hi:[1,0]
	v_pk_fma_f32 v[28:29], v[8:9], v[56:57], v[28:29] op_sel_hi:[0,1,1]
	v_pk_fma_f32 v[40:41], v[30:31], v[30:31], v[40:41]
	v_pk_mul_f32 v[38:39], v[28:29], v[28:29]
	v_pk_add_f32 v[50:51], v[50:51], v[40:41]
	v_pk_fma_f32 v[38:39], v[32:33], v[32:33], v[38:39]
	v_pk_add_f32 v[40:41], v[50:51], v[40:41] op_sel:[0,1] op_sel_hi:[1,0]
	v_pk_fma_f32 v[16:17], v[8:9], v[58:59], v[16:17] op_sel_hi:[0,1,1]
	v_pk_add_f32 v[40:41], v[40:41], v[38:39]
	v_pk_fma_f32 v[20:21], v[8:9], v[42:43], v[20:21] op_sel_hi:[0,1,1]
	v_pk_mul_f32 v[42:43], v[16:17], v[16:17]
	v_pk_add_f32 v[38:39], v[40:41], v[38:39] op_sel:[0,1] op_sel_hi:[1,0]
	v_pk_fma_f32 v[18:19], v[8:9], v[60:61], v[18:19] op_sel_hi:[0,1,1]
	v_pk_fma_f32 v[42:43], v[20:21], v[20:21], v[42:43]
	v_pk_fma_f32 v[22:23], v[8:9], v[44:45], v[22:23] op_sel_hi:[0,1,1]
	v_pk_mul_f32 v[40:41], v[18:19], v[18:19]
	v_pk_add_f32 v[38:39], v[38:39], v[42:43]
	v_pk_fma_f32 v[40:41], v[22:23], v[22:23], v[40:41]
	v_pk_add_f32 v[38:39], v[38:39], v[42:43] op_sel:[0,1] op_sel_hi:[1,0]
	v_pk_fma_f32 v[14:15], v[8:9], v[46:47], v[14:15] op_sel_hi:[0,1,1]
	v_pk_fma_f32 v[8:9], v[8:9], v[62:63], v[12:13] op_sel_hi:[0,1,1]
	v_pk_add_f32 v[38:39], v[38:39], v[40:41]
	v_pk_mul_f32 v[12:13], v[8:9], v[8:9]
	v_pk_add_f32 v[38:39], v[38:39], v[40:41] op_sel:[0,1] op_sel_hi:[1,0]
	v_pk_fma_f32 v[12:13], v[14:15], v[14:15], v[12:13]
	v_pk_mul_f32 v[10:11], v[2:3], v[2:3]
	v_pk_add_f32 v[38:39], v[38:39], v[12:13]
	v_pk_fma_f32 v[10:11], v[4:5], v[4:5], v[10:11]
	v_pk_add_f32 v[12:13], v[38:39], v[12:13] op_sel:[0,1] op_sel_hi:[1,0]
	v_readlane_b32 s30, v253, 53
	v_pk_add_f32 v[12:13], v[12:13], v[10:11]
	s_nop 0
	v_pk_add_f32 v[10:11], v[12:13], v[10:11] op_sel:[0,1] op_sel_hi:[1,0]
	s_nop 0
	v_mov_b32_e32 v0, v10
	s_nop 1
	v_permlane32_swap_b32_e32 v10, v0
	v_add_f32_e32 v0, v10, v0
	v_fmamk_f32 v0, v0, 0x3c800000, v139
	v_cmp_gt_f32_e32 vcc, s71, v0
	v_mul_f32_e32 v10, 0x4b800000, v0
	s_nop 0
	v_cndmask_b32_e32 v0, v0, v10, vcc
	v_rsq_f32_e32 v0, v0
	s_nop 0
	v_mul_f32_e32 v10, 0x45800000, v0
	v_cndmask_b32_e32 v0, v0, v10, vcc
	v_pk_mul_f32 v[10:11], v[68:69], v[0:1] op_sel_hi:[1,0]
	v_pk_mul_f32 v[12:13], v[64:65], v[0:1] op_sel_hi:[1,0]
	v_pk_mul_f32 v[24:25], v[24:25], v[0:1] op_sel_hi:[1,0]
	v_pk_mul_f32 v[20:21], v[20:21], v[0:1] op_sel_hi:[1,0]
	v_pk_mul_f32 v[16:17], v[16:17], v[0:1] op_sel_hi:[1,0]
	v_pk_mul_f32 v[14:15], v[14:15], v[0:1] op_sel_hi:[1,0]
	v_pk_mul_f32 v[4:5], v[4:5], v[0:1] op_sel_hi:[1,0]
	v_pk_mul_f32 v[2:3], v[2:3], v[0:1] op_sel_hi:[1,0]
	global_load_dwordx4 v[72:75], v70, s[0:1] offset:128
	global_load_dwordx4 v[76:79], v70, s[0:1] offset:32
	global_load_dwordx4 v[80:83], v70, s[0:1] offset:160
	global_load_dwordx4 v[84:87], v70, s[0:1] offset:64
	global_load_dwordx4 v[112:115], v70, s[0:1] offset:192
	global_load_dwordx4 v[116:119], v70, s[0:1] offset:96
	global_load_dwordx4 v[120:123], v70, s[0:1] offset:224
	s_waitcnt vmcnt(0)
; __device__ __forceinline__ unsigned cvtpk(float lo, float hi) { f32x2_t v = {lo, hi}; bf16x2_t b = __builtin_convertvector(v, bf16x2_t); return __builtin_bit_cast(unsigned, b); }
; __device__ __forceinline__ void nsa_item(const NsaArgs& A, int b, int tl, LAS unsigned char* lds, int tid) {
;     ...
; #pragma unroll
;         for (int g = 0; g < 4; ++g) { const int d0 = 8 * g + 4 * hh;
;             u32x2 wa; wa.x = cvtpk(of0[4 * g] * rs * go[d0], of0[4 * g + 1] * rs * go[d0 + 1]); wa.y = cvtpk(of0[4 * g + 2] * rs * go[d0 + 2], of0[4 * g + 3] * rs * go[d0 + 3]);
;             *(u32x2*)(dst + d0) = wa;
;             u32x2 wb; wb.x = cvtpk(of1[4 * g] * rs * go[32 + d0], of1[4 * g + 1] * rs * go[32 + d0 + 1]); wb.y = cvtpk(of1[4 * g + 2] * rs * go[32 + d0 + 2], of1[4 * g + 3] * rs * go[32 + d0 + 3]);
;             *(u32x2*)(dst + 32 + d0) = wb; }
;     }
;     __syncthreads();
	v_pk_mul_f32 v[10:11], v[34:35], v[10:11]
	v_pk_mul_f32 v[12:13], v[36:37], v[12:13]
	v_cvt_pk_bf16_f32 v10, v10, v11
	v_cvt_pk_bf16_f32 v11, v12, v13
	global_store_dwordx2 v[6:7], v[10:11], off
	v_pk_mul_f32 v[10:11], v[72:73], v[24:25]
	v_pk_mul_f32 v[24:25], v[48:49], v[0:1] op_sel_hi:[1,0]
	v_cvt_pk_bf16_f32 v10, v10, v11
	v_pk_mul_f32 v[12:13], v[74:75], v[24:25]
	v_pk_mul_f32 v[24:25], v[30:31], v[0:1] op_sel_hi:[1,0]
	v_cvt_pk_bf16_f32 v11, v12, v13
	global_store_dwordx2 v[6:7], v[10:11], off offset:64
	v_pk_mul_f32 v[10:11], v[24:25], v[76:77]
	v_pk_mul_f32 v[24:25], v[32:33], v[0:1] op_sel_hi:[1,0]
	v_cvt_pk_bf16_f32 v10, v10, v11
	v_pk_mul_f32 v[12:13], v[24:25], v[78:79]
	v_pk_mul_f32 v[24:25], v[26:27], v[0:1] op_sel_hi:[1,0]
	v_cvt_pk_bf16_f32 v11, v12, v13
	global_store_dwordx2 v[6:7], v[10:11], off offset:16
	v_pk_mul_f32 v[10:11], v[24:25], v[80:81]
	v_pk_mul_f32 v[24:25], v[28:29], v[0:1] op_sel_hi:[1,0]
	v_cvt_pk_bf16_f32 v10, v10, v11
	v_pk_mul_f32 v[12:13], v[24:25], v[82:83]
	s_nop 0
	v_cvt_pk_bf16_f32 v11, v12, v13
	global_store_dwordx2 v[6:7], v[10:11], off offset:80
	v_pk_mul_f32 v[10:11], v[20:21], v[84:85]
	v_pk_mul_f32 v[20:21], v[22:23], v[0:1] op_sel_hi:[1,0]
	v_cvt_pk_bf16_f32 v10, v10, v11
	v_pk_mul_f32 v[12:13], v[20:21], v[86:87]
	s_nop 0
	v_cvt_pk_bf16_f32 v11, v12, v13
	global_store_dwordx2 v[6:7], v[10:11], off offset:32
	v_pk_mul_f32 v[10:11], v[16:17], v[112:113]
	v_pk_mul_f32 v[16:17], v[18:19], v[0:1] op_sel_hi:[1,0]
	v_cvt_pk_bf16_f32 v10, v10, v11
	v_pk_mul_f32 v[12:13], v[16:17], v[114:115]
	s_nop 0
	v_cvt_pk_bf16_f32 v11, v12, v13
	global_store_dwordx2 v[6:7], v[10:11], off offset:96
	v_pk_mul_f32 v[10:11], v[14:15], v[116:117]
	v_pk_mul_f32 v[4:5], v[4:5], v[118:119]
	v_cvt_pk_bf16_f32 v10, v10, v11
	v_cvt_pk_bf16_f32 v11, v4, v5
	global_store_dwordx2 v[6:7], v[10:11], off offset:48
	v_pk_mul_f32 v[4:5], v[8:9], v[0:1] op_sel_hi:[1,0]
	v_pk_mul_f32 v[4:5], v[4:5], v[120:121]
	v_pk_mul_f32 v[2:3], v[2:3], v[122:123]
	v_cvt_pk_bf16_f32 v4, v4, v5
	v_cvt_pk_bf16_f32 v5, v2, v3
	global_store_dwordx2 v[6:7], v[4:5], off offset:112
	s_barrier
